# v26: v25 + nt policy for the layer-0 FFN1 residual epilogue reads of the input x (its last use)
# baseline (speedup 1.0000x reference)
; #define PG8_LAS __attribute__((address_space(3)))
;     __device__ __forceinline__ void fused(f32x4 (&acc)[2][2][4][2], const Unit& u, int wr, int wc, int fr, int fq, PG8_LAS unsigned char* lds, int wid, int lane) const {
;         float scl = scale; asm volatile("" : "+v"(scl)); const int row0 = u.pm * BM + wr * 64 + fr, col0 = u.pn * BM + wc * 32 + 4 * fq;
;         PG8_LAS float* P = (PG8_LAS float*)lds;
; #pragma unroll
;         for (int ai = 0; ai < 2; ++ai) { f32x4 xv[4][2][2];
; #pragma unroll
;             for (int m = 0; m < 4; ++m)
; #pragma unroll
;                 for (int bj = 0; bj < 2; ++bj)
; #pragma unroll
;                     for (int n = 0; n < 2; ++n) xv[m][bj][n] = *(const f32x4*)(xin + (size_t)(row0 + ai * HALF + m * 16) * 1024 + col0 + bj * HALF + n * 16);
.LBB0_411:
	v_readlane_b32 s3, v255, 0
	s_lshl_b32 s2, s20, 5
	s_lshl_b32 s4, s3, 8
	s_lshl_b32 s3, s96, 8
	v_bfe_u32 v193, v192, 4, 2
	s_add_i32 s30, s30, s4
	s_or_b32 s2, s2, s3
	v_or_b32_e32 v182, s30, v136
	v_lshl_or_b32 v180, v193, 2, s2
	v_ashrrev_i32_e32 v181, 31, v180
	v_ashrrev_i32_e32 v183, 31, v182
	v_lshl_add_u64 v[184:185], v[180:181], 2, s[0:1]
	v_lshlrev_b64 v[130:131], 12, v[182:183]
	v_or_b32_e32 v190, 16, v182
	v_mov_b32_e32 v178, 0.5
	v_lshl_add_u64 v[130:131], v[184:185], 0, v[130:131]
	v_ashrrev_i32_e32 v191, 31, v190
	s_barrier
	v_readlane_b32 s87, v254, 58
	s_nop 3
	s_cmp_eq_u32 s87, 0
	s_cbranch_scc0 .Lx2d_0
	global_load_dwordx4 v[210:213], v[130:131], off nt
	s_branch .Lx2j_0
.Lx2d_0:
	global_load_dwordx4 v[210:213], v[130:131], off
.Lx2j_0:
	s_cmp_eq_u32 s87, 0
	s_cbranch_scc0 .Lx2d_1
	global_load_dwordx4 v[214:217], v[130:131], off offset:64 nt
	s_branch .Lx2j_1
.Lx2d_1:
	global_load_dwordx4 v[214:217], v[130:131], off offset:64
.Lx2j_1:
	s_cmp_eq_u32 s87, 0
	s_cbranch_scc0 .Lx2d_2
	global_load_dwordx4 v[218:221], v[130:131], off offset:512 nt
	s_branch .Lx2j_2
.Lx2d_2:
	global_load_dwordx4 v[218:221], v[130:131], off offset:512
.Lx2j_2:
	s_cmp_eq_u32 s87, 0
	s_cbranch_scc0 .Lx2d_3
	global_load_dwordx4 v[242:245], v[130:131], off offset:576 nt
	s_branch .Lx2j_3
.Lx2d_3:
	global_load_dwordx4 v[242:245], v[130:131], off offset:576
.Lx2j_3:
	v_lshlrev_b64 v[130:131], 12, v[190:191]
	v_or_b32_e32 v188, 32, v182
	v_lshl_add_u64 v[130:131], v[184:185], 0, v[130:131]
	v_ashrrev_i32_e32 v189, 31, v188
	s_cmp_eq_u32 s87, 0
	s_cbranch_scc0 .Lx2d_4
	global_load_dwordx4 v[174:177], v[130:131], off nt
	s_branch .Lx2j_4
.Lx2d_4:
	global_load_dwordx4 v[174:177], v[130:131], off
.Lx2j_4:
	s_cmp_eq_u32 s87, 0
	s_cbranch_scc0 .Lx2d_5
	global_load_dwordx4 v[170:173], v[130:131], off offset:64 nt
	s_branch .Lx2j_5
.Lx2d_5:
	global_load_dwordx4 v[170:173], v[130:131], off offset:64
.Lx2j_5:
	s_cmp_eq_u32 s87, 0
	s_cbranch_scc0 .Lx2d_6
	global_load_dwordx4 v[166:169], v[130:131], off offset:512 nt
	s_branch .Lx2j_6
.Lx2d_6:
	global_load_dwordx4 v[166:169], v[130:131], off offset:512
.Lx2j_6:
	s_cmp_eq_u32 s87, 0
	s_cbranch_scc0 .Lx2d_7
	global_load_dwordx4 v[162:165], v[130:131], off offset:576 nt
	s_branch .Lx2j_7
.Lx2d_7:
	global_load_dwordx4 v[162:165], v[130:131], off offset:576
.Lx2j_7:
	v_lshlrev_b64 v[130:131], 12, v[188:189]
	v_or_b32_e32 v186, 48, v182
	v_lshl_add_u64 v[130:131], v[184:185], 0, v[130:131]
	v_ashrrev_i32_e32 v187, 31, v186
	s_cmp_eq_u32 s87, 0
	s_cbranch_scc0 .Lx2d_8
	global_load_dwordx4 v[158:161], v[130:131], off nt
	s_branch .Lx2j_8
.Lx2d_8:
	global_load_dwordx4 v[158:161], v[130:131], off
.Lx2j_8:
	s_cmp_eq_u32 s87, 0
	s_cbranch_scc0 .Lx2d_9
	global_load_dwordx4 v[154:157], v[130:131], off offset:64 nt
	s_branch .Lx2j_9
.Lx2d_9:
	global_load_dwordx4 v[154:157], v[130:131], off offset:64
.Lx2j_9:
	s_cmp_eq_u32 s87, 0
	s_cbranch_scc0 .Lx2d_10
	global_load_dwordx4 v[150:153], v[130:131], off offset:512 nt
	s_branch .Lx2j_10
.Lx2d_10:
	global_load_dwordx4 v[150:153], v[130:131], off offset:512
.Lx2j_10:
	s_cmp_eq_u32 s87, 0
	s_cbranch_scc0 .Lx2d_11
	global_load_dwordx4 v[146:149], v[130:131], off offset:576 nt
	s_branch .Lx2j_11
.Lx2d_11:
	global_load_dwordx4 v[146:149], v[130:131], off offset:576
.Lx2j_11:
	v_lshlrev_b64 v[130:131], 12, v[186:187]
	v_lshl_add_u64 v[130:131], v[184:185], 0, v[130:131]
	s_cmp_eq_u32 s87, 0
	s_cbranch_scc0 .Lx2d_12
	global_load_dwordx4 v[142:145], v[130:131], off nt
	s_branch .Lx2j_12
.Lx2d_12:
	global_load_dwordx4 v[142:145], v[130:131], off
.Lx2j_12:
	s_cmp_eq_u32 s87, 0
	s_cbranch_scc0 .Lx2d_13
	global_load_dwordx4 v[138:141], v[130:131], off offset:64 nt
	s_branch .Lx2j_13
; __device__ __forceinline__ unsigned cvt_pk_bf16(float lo, float hi) { unsigned r; asm volatile("v_cvt_pk_bf16_f32 %0, %1, %2" : "=v"(r) : "v"(lo), "v"(hi)); return r; }
; __device__ __forceinline__ float bperm(float v, int srclane) { return __int_as_float(__builtin_amdgcn_ds_bpermute(srclane << 2, __float_as_int(v))); }
; __device__ __forceinline__ float bperm(float v, int srclane) { return __int_as_float(__builtin_amdgcn_ds_bpermute(srclane << 2, __float_as_int(v))); }
;     __device__ __forceinline__ void fused(f32x4 (&acc)[2][2][4][2], const Unit& u, int wr, int wc, int fr, int fq, PG8_LAS unsigned char* lds, int wid, int lane) const {
;     ...
;                     for (int n = 0; n < 2; ++n) xv[m][bj][n] = *(const f32x4*)(xin + (size_t)(row0 + ai * HALF + m * 16) * 1024 + col0 + bj * HALF + n * 16);
;             __builtin_amdgcn_sched_barrier(0);
; #pragma unroll
;             for (int m = 0; m < 4; ++m) { const int row = row0 + ai * HALF + m * 16; float q = 0.f;
; #pragma unroll
;                 for (int bj = 0; bj < 2; ++bj)
; #pragma unroll
;                     for (int n = 0; n < 2; ++n) { const size_t off = (size_t)row * 1024 + col0 + bj * HALF + n * 16;
;                         f32x4 v = xv[m][bj][n] + acc[ai][bj][m][n] * scl; *(f32x4*)(x + off) = v;
;                         u32x2 w; w.x = cvt_pk_bf16(v[0], v[1]); w.y = cvt_pk_bf16(v[2], v[3]); *(u32x2*)(xb + off) = w;
;                         q += (v[0] * v[0] + v[1] * v[1]) + (v[2] * v[2] + v[3] * v[3]); }
;                 q += bperm(q, (fr + 16 * fq) ^ 16); q += bperm(q, (fr + 16 * fq) ^ 32);
;                 if (fq == 0) P[(ai * HALF + wr * 64 + m * 16 + fr) * 4 + wc] = q; }
.Lx2d_13:
	global_load_dwordx4 v[138:141], v[130:131], off offset:64
.Lx2j_13:
	s_cmp_eq_u32 s87, 0
	s_cbranch_scc0 .Lx2d_14
	global_load_dwordx4 v[134:137], v[130:131], off offset:512 nt
	s_branch .Lx2j_14
.Lx2d_14:
	global_load_dwordx4 v[134:137], v[130:131], off offset:512
.Lx2j_14:
	s_nop 0
	s_cmp_eq_u32 s87, 0
	s_cbranch_scc0 .Lx2d_15
	global_load_dwordx4 v[130:133], v[130:131], off offset:576 nt
	s_branch .Lx2j_15
.Lx2d_15:
	global_load_dwordx4 v[130:133], v[130:131], off offset:576
.Lx2j_15:
	v_and_b32_e32 v64, 63, v192
	s_lshl_b32 s2, s20, 2
	v_lshlrev_b32_e32 v192, 6, v193
	s_add_i32 s2, s2, 0
	v_bitop3_b32 v193, v192, 64, v194 bitop3:0x36
	v_bitop3_b32 v192, v192, s93, v194 bitop3:0x36
	v_cmp_gt_u32_e32 vcc, 16, v64
	v_lshlrev_b64 v[194:195], 10, v[182:183]
	v_lshl_add_u64 v[194:195], v[194:195], 0, v[180:181]
	s_waitcnt vmcnt(0)
	v_pk_fma_f32 v[128:129], v[128:129], v[178:179], v[212:213] op_sel_hi:[1,0,1]
	v_pk_fma_f32 v[126:127], v[126:127], v[178:179], v[210:211] op_sel_hi:[1,0,1]
	v_lshl_add_u64 v[210:211], v[194:195], 2, s[76:77]
	global_store_dwordx4 v[210:211], v[126:129], off
	v_cvt_pk_bf16_f32 v212, v126, v127
	v_lshlrev_b64 v[194:195], 1, v[194:195]
	v_lshl_add_u64 v[222:223], s[26:27], 0, v[194:195]
	v_mul_f32_e32 v127, v127, v127
	v_fmac_f32_e32 v127, v126, v126
	v_mul_f32_e32 v126, v129, v129
	v_fmac_f32_e32 v126, v128, v128
	v_pk_fma_f32 v[124:125], v[124:125], v[178:179], v[216:217] op_sel_hi:[1,0,1]
	v_pk_fma_f32 v[122:123], v[122:123], v[178:179], v[214:215] op_sel_hi:[1,0,1]
	v_cvt_pk_bf16_f32 v213, v128, v129
	global_store_dwordx2 v[222:223], v[212:213], off
	v_add_f32_e32 v183, v127, v126
	global_store_dwordx4 v[210:211], v[122:125], off offset:64
	v_cvt_pk_bf16_f32 v126, v122, v123
	v_or_b32_e32 v128, 32, v194
	v_mov_b32_e32 v129, v195
	v_mul_f32_e32 v123, v123, v123
	v_fmac_f32_e32 v123, v122, v122
	v_mul_f32_e32 v122, v125, v125
	v_fmac_f32_e32 v122, v124, v124
	v_lshl_add_u64 v[128:129], s[26:27], 0, v[128:129]
	v_add_f32_e32 v122, v123, v122
	v_pk_fma_f32 v[120:121], v[120:121], v[178:179], v[220:221] op_sel_hi:[1,0,1]
	v_pk_fma_f32 v[118:119], v[118:119], v[178:179], v[218:219] op_sel_hi:[1,0,1]
	v_cvt_pk_bf16_f32 v127, v124, v125
	global_store_dwordx2 v[128:129], v[126:127], off
	v_add_f32_e32 v126, v183, v122
	global_store_dwordx4 v[210:211], v[118:121], off offset:512
	v_cvt_pk_bf16_f32 v122, v118, v119
	v_pk_fma_f32 v[116:117], v[116:117], v[178:179], v[244:245] op_sel_hi:[1,0,1]
	v_pk_fma_f32 v[114:115], v[114:115], v[178:179], v[242:243] op_sel_hi:[1,0,1]
	v_mul_f32_e32 v119, v119, v119
	v_fmac_f32_e32 v119, v118, v118
	v_mul_f32_e32 v118, v121, v121
	v_fmac_f32_e32 v118, v120, v120
	v_cvt_pk_bf16_f32 v123, v120, v121
	v_add_f32_e32 v118, v119, v118
	v_mul_f32_e32 v119, v115, v115
	v_mul_f32_e32 v120, v117, v117
	v_fmac_f32_e32 v119, v114, v114
	v_fmac_f32_e32 v120, v116, v116
	v_add_f32_e32 v118, v118, v126
	v_add_f32_e32 v119, v119, v120
	v_add_f32_e32 v120, v119, v118
	ds_bpermute_b32 v121, v193, v120
	v_or_b32_e32 v124, 0x100, v194
	v_mov_b32_e32 v125, v195
	v_lshl_add_u64 v[124:125], s[26:27], 0, v[124:125]
	global_store_dwordx2 v[124:125], v[122:123], off
	global_store_dwordx4 v[210:211], v[114:117], off offset:576
	v_cvt_pk_bf16_f32 v118, v114, v115
	v_or_b32_e32 v194, 0x120, v194
	v_cvt_pk_bf16_f32 v119, v116, v117
	v_lshl_add_u32 v122, v179, 4, s2
	s_waitcnt lgkmcnt(0)
	v_add_f32_e32 v114, v120, v121
	ds_bpermute_b32 v115, v192, v114
	v_lshl_add_u64 v[116:117], s[26:27], 0, v[194:195]
	global_store_dwordx2 v[116:117], v[118:119], off
	s_and_saveexec_b64 s[2:3], vcc
	s_cbranch_execz .LBB0_413
	s_waitcnt lgkmcnt(0)
	v_add_f32_e32 v114, v114, v115
	ds_write_b32 v122, v114

; __device__ __forceinline__ unsigned cvt_pk_bf16(float lo, float hi) { unsigned r; asm volatile("v_cvt_pk_bf16_f32 %0, %1, %2" : "=v"(r) : "v"(lo), "v"(hi)); return r; }
; __device__ __forceinline__ float bperm(float v, int srclane) { return __int_as_float(__builtin_amdgcn_ds_bpermute(srclane << 2, __float_as_int(v))); }
; __device__ __forceinline__ float bperm(float v, int srclane) { return __int_as_float(__builtin_amdgcn_ds_bpermute(srclane << 2, __float_as_int(v))); }
;     __device__ __forceinline__ void fused(f32x4 (&acc)[2][2][4][2], const Unit& u, int wr, int wc, int fr, int fq, PG8_LAS unsigned char* lds, int wid, int lane) const {
;     ...
;         for (int ai = 0; ai < 2; ++ai) { f32x4 xv[4][2][2];
; #pragma unroll
;             for (int m = 0; m < 4; ++m)
; #pragma unroll
;                 for (int bj = 0; bj < 2; ++bj)
; #pragma unroll
;                     for (int n = 0; n < 2; ++n) xv[m][bj][n] = *(const f32x4*)(xin + (size_t)(row0 + ai * HALF + m * 16) * 1024 + col0 + bj * HALF + n * 16);
;             __builtin_amdgcn_sched_barrier(0);
; #pragma unroll
;             for (int m = 0; m < 4; ++m) { const int row = row0 + ai * HALF + m * 16; float q = 0.f;
; #pragma unroll
;                 for (int bj = 0; bj < 2; ++bj)
; #pragma unroll
;                     for (int n = 0; n < 2; ++n) { const size_t off = (size_t)row * 1024 + col0 + bj * HALF + n * 16;
;                         f32x4 v = xv[m][bj][n] + acc[ai][bj][m][n] * scl; *(f32x4*)(x + off) = v;
;                         u32x2 w; w.x = cvt_pk_bf16(v[0], v[1]); w.y = cvt_pk_bf16(v[2], v[3]); *(u32x2*)(xb + off) = w;
;                         q += (v[0] * v[0] + v[1] * v[1]) + (v[2] * v[2] + v[3] * v[3]); }
;                 q += bperm(q, (fr + 16 * fq) ^ 16); q += bperm(q, (fr + 16 * fq) ^ 32);
;                 if (fq == 0) P[(ai * HALF + wr * 64 + m * 16 + fr) * 4 + wc] = q; }
.LBB0_419:
	s_or_b64 exec, exec, s[2:3]
	v_add_u32_e32 v140, 0x80, v182
	v_ashrrev_i32_e32 v141, 31, v140
	s_waitcnt lgkmcnt(0)
	v_lshlrev_b64 v[66:67], 12, v[140:141]
	v_add_u32_e32 v120, 0x90, v182
	v_lshl_add_u64 v[66:67], v[184:185], 0, v[66:67]
	v_ashrrev_i32_e32 v121, 31, v120
	s_cmp_eq_u32 s87, 0
	s_cbranch_scc0 .Lx2d_16
	global_load_dwordx4 v[124:127], v[66:67], off nt
	s_branch .Lx2j_16
.Lx2d_16:
	global_load_dwordx4 v[124:127], v[66:67], off
.Lx2j_16:
	s_cmp_eq_u32 s87, 0
	s_cbranch_scc0 .Lx2d_17
	global_load_dwordx4 v[128:131], v[66:67], off offset:64 nt
	s_branch .Lx2j_17
.Lx2d_17:
	global_load_dwordx4 v[128:131], v[66:67], off offset:64
.Lx2j_17:
	s_cmp_eq_u32 s87, 0
	s_cbranch_scc0 .Lx2d_18
	global_load_dwordx4 v[132:135], v[66:67], off offset:512 nt
	s_branch .Lx2j_18
.Lx2d_18:
	global_load_dwordx4 v[132:135], v[66:67], off offset:512
.Lx2j_18:
	s_cmp_eq_u32 s87, 0
	s_cbranch_scc0 .Lx2d_19
	global_load_dwordx4 v[136:139], v[66:67], off offset:576 nt
	s_branch .Lx2j_19
.Lx2d_19:
	global_load_dwordx4 v[136:139], v[66:67], off offset:576
.Lx2j_19:
	v_lshlrev_b64 v[66:67], 12, v[120:121]
	v_add_u32_e32 v116, 0xa0, v182
	v_lshl_add_u64 v[66:67], v[184:185], 0, v[66:67]
	v_ashrrev_i32_e32 v117, 31, v116
	s_cmp_eq_u32 s87, 0
	s_cbranch_scc0 .Lx2d_20
	global_load_dwordx4 v[110:113], v[66:67], off nt
	s_branch .Lx2j_20
.Lx2d_20:
	global_load_dwordx4 v[110:113], v[66:67], off
.Lx2j_20:
	s_cmp_eq_u32 s87, 0
	s_cbranch_scc0 .Lx2d_21
	global_load_dwordx4 v[106:109], v[66:67], off offset:64 nt
	s_branch .Lx2j_21
.Lx2d_21:
	global_load_dwordx4 v[106:109], v[66:67], off offset:64
.Lx2j_21:
	s_cmp_eq_u32 s87, 0
	s_cbranch_scc0 .Lx2d_22
	global_load_dwordx4 v[102:105], v[66:67], off offset:512 nt
	s_branch .Lx2j_22
.Lx2d_22:
	global_load_dwordx4 v[102:105], v[66:67], off offset:512
.Lx2j_22:
	s_cmp_eq_u32 s87, 0
	s_cbranch_scc0 .Lx2d_23
	global_load_dwordx4 v[98:101], v[66:67], off offset:576 nt
	s_branch .Lx2j_23
.Lx2d_23:
	global_load_dwordx4 v[98:101], v[66:67], off offset:576
.Lx2j_23:
	v_lshlrev_b64 v[66:67], 12, v[116:117]
	v_add_u32_e32 v114, 0xb0, v182
	v_lshl_add_u64 v[66:67], v[184:185], 0, v[66:67]
	v_ashrrev_i32_e32 v115, 31, v114
	s_cmp_eq_u32 s87, 0
	s_cbranch_scc0 .Lx2d_24
	global_load_dwordx4 v[94:97], v[66:67], off nt
	s_branch .Lx2j_24
.Lx2d_24:
	global_load_dwordx4 v[94:97], v[66:67], off
.Lx2j_24:
	s_cmp_eq_u32 s87, 0
	s_cbranch_scc0 .Lx2d_25
	global_load_dwordx4 v[90:93], v[66:67], off offset:64 nt
	s_branch .Lx2j_25
.Lx2d_25:
	global_load_dwordx4 v[90:93], v[66:67], off offset:64
.Lx2j_25:
	s_cmp_eq_u32 s87, 0
	s_cbranch_scc0 .Lx2d_26
	global_load_dwordx4 v[86:89], v[66:67], off offset:512 nt
	s_branch .Lx2j_26
.Lx2d_26:
	global_load_dwordx4 v[86:89], v[66:67], off offset:512
.Lx2j_26:
	s_cmp_eq_u32 s87, 0
	s_cbranch_scc0 .Lx2d_27
	global_load_dwordx4 v[82:85], v[66:67], off offset:576 nt
	s_branch .Lx2j_27
.Lx2d_27:
	global_load_dwordx4 v[82:85], v[66:67], off offset:576
.Lx2j_27:
	v_lshlrev_b64 v[66:67], 12, v[114:115]
	v_lshl_add_u64 v[66:67], v[184:185], 0, v[66:67]
	s_cmp_eq_u32 s87, 0
	s_cbranch_scc0 .Lx2d_28
	global_load_dwordx4 v[78:81], v[66:67], off nt
	s_branch .Lx2j_28
.Lx2d_28:
	global_load_dwordx4 v[78:81], v[66:67], off
.Lx2j_28:
	s_cmp_eq_u32 s87, 0
	s_cbranch_scc0 .Lx2d_29
	global_load_dwordx4 v[74:77], v[66:67], off offset:64 nt
	s_branch .Lx2j_29
.Lx2d_29:
	global_load_dwordx4 v[74:77], v[66:67], off offset:64
.Lx2j_29:
	s_cmp_eq_u32 s87, 0
	s_cbranch_scc0 .Lx2d_30
	global_load_dwordx4 v[70:73], v[66:67], off offset:512 nt
	s_branch .Lx2j_30
.Lx2d_30:
	global_load_dwordx4 v[70:73], v[66:67], off offset:512
.Lx2j_30:
	s_nop 0
	s_cmp_eq_u32 s87, 0
	s_cbranch_scc0 .Lx2d_31
	global_load_dwordx4 v[66:69], v[66:67], off offset:576 nt
	s_branch .Lx2j_31
.Lx2d_31:
	global_load_dwordx4 v[66:69], v[66:67], off offset:576
.Lx2j_31:
	v_lshlrev_b64 v[140:141], 10, v[140:141]
	v_lshl_add_u64 v[140:141], v[140:141], 0, v[180:181]
	s_waitcnt vmcnt(15)
	v_pk_fma_f32 v[62:63], v[62:63], v[118:119], v[126:127]
	v_pk_fma_f32 v[60:61], v[60:61], v[178:179], v[124:125]
	v_lshl_add_u64 v[124:125], v[140:141], 2, s[76:77]
	global_store_dwordx4 v[124:125], v[60:63], off
	v_cvt_pk_bf16_f32 v126, v60, v61
	v_lshlrev_b64 v[140:141], 1, v[140:141]
	v_lshl_add_u64 v[142:143], s[26:27], 0, v[140:141]
	v_mul_f32_e32 v61, v61, v61
	v_fmac_f32_e32 v61, v60, v60
	v_mul_f32_e32 v60, v63, v63
	v_fmac_f32_e32 v60, v62, v62
	s_waitcnt vmcnt(15)
	v_pk_fma_f32 v[58:59], v[58:59], v[118:119], v[130:131]
	v_pk_fma_f32 v[56:57], v[56:57], v[178:179], v[128:129]
	v_cvt_pk_bf16_f32 v127, v62, v63
	global_store_dwordx2 v[142:143], v[126:127], off
	v_add_f32_e32 v123, v61, v60
	global_store_dwordx4 v[124:125], v[56:59], off offset:64
	v_cvt_pk_bf16_f32 v60, v56, v57
	v_or_b32_e32 v62, 32, v140
	v_mov_b32_e32 v63, v141
	v_mul_f32_e32 v57, v57, v57
	v_fmac_f32_e32 v57, v56, v56
	v_mul_f32_e32 v56, v59, v59
	v_fmac_f32_e32 v56, v58, v58
	v_lshl_add_u64 v[62:63], s[26:27], 0, v[62:63]
	v_add_f32_e32 v56, v57, v56
	s_waitcnt vmcnt(16)
	v_pk_fma_f32 v[54:55], v[54:55], v[118:119], v[134:135]
	v_pk_fma_f32 v[52:53], v[52:53], v[178:179], v[132:133]
	v_cvt_pk_bf16_f32 v61, v58, v59
	global_store_dwordx2 v[62:63], v[60:61], off
	v_add_f32_e32 v60, v123, v56
	global_store_dwordx4 v[124:125], v[52:55], off offset:512
	v_cvt_pk_bf16_f32 v56, v52, v53
	s_waitcnt vmcnt(17)
	v_pk_fma_f32 v[50:51], v[50:51], v[118:119], v[138:139]
	v_pk_fma_f32 v[48:49], v[48:49], v[178:179], v[136:137]
	v_mul_f32_e32 v53, v53, v53
	v_fmac_f32_e32 v53, v52, v52
	v_mul_f32_e32 v52, v55, v55
	v_fmac_f32_e32 v52, v54, v54
	v_cvt_pk_bf16_f32 v57, v54, v55
	v_add_f32_e32 v52, v53, v52
	v_mul_f32_e32 v53, v49, v49
	v_mul_f32_e32 v54, v51, v51
	v_fmac_f32_e32 v53, v48, v48
	v_fmac_f32_e32 v54, v50, v50
	v_add_f32_e32 v52, v60, v52
	v_add_f32_e32 v53, v53, v54
	v_add_f32_e32 v54, v52, v53
	ds_bpermute_b32 v55, v193, v54
	v_or_b32_e32 v58, 0x100, v140
	v_mov_b32_e32 v59, v141
	v_lshl_add_u64 v[52:53], s[26:27], 0, v[58:59]
	global_store_dwordx2 v[52:53], v[56:57], off
	global_store_dwordx4 v[124:125], v[48:51], off offset:576
	v_cvt_pk_bf16_f32 v52, v48, v49
	v_or_b32_e32 v140, 0x120, v140
	v_cvt_pk_bf16_f32 v53, v50, v51
	s_waitcnt lgkmcnt(0)
	v_add_f32_e32 v48, v54, v55
	ds_bpermute_b32 v49, v192, v48
	v_lshl_add_u64 v[50:51], s[26:27], 0, v[140:141]
	global_store_dwordx2 v[50:51], v[52:53], off
	s_and_saveexec_b64 s[2:3], vcc
	s_cbranch_execz .LBB0_421
	s_waitcnt lgkmcnt(0)
	v_add_f32_e32 v48, v48, v49
	ds_write_b32 v122, v48 offset:2048
